# GLA chunk-summary units: the 12 fragment ds_read_b128 of the 8 KV^T MFMAs issued ahead with counted lgkmcnt waits
# baseline (speedup 1.0000x reference)
; #define LAS __attribute__((address_space(3)))
; __device__ __forceinline__ unsigned short f2bf(float f) { return (unsigned short)(cvt_pk_bf16(f, 0.f) & 0xffffu); }
; __device__ __forceinline__ void gla_p1(CArgs& a, int l, int cc, int h, LAS float* L, int dup, bool stagew) {
;     ...
;         oqf[dd] = q * __expf(cf); oqb[dd] = q * __expf(cb); okf[dd] = k * __expf(-cf); okb[dd] = k * __expf(-cb);
;         *(LAS unsigned short*)(B + GB_QDF + (d * HS + lane) * 2) = f2bf(k * __expf(totf - cf));
;         *(LAS unsigned short*)(B + GB_QDB + (d * HS + lane) * 2) = f2bf(k * __expf(totb - cb));
;         if (lane == 0) { DEC[(size_t)slot * 64 + d] = __expf(totf); DEC[(size_t)(slot + 1) * 64 + d] = __expf(totb); } }
;     { u32x4 w;
;       w.x = cvt_pk_bf16(oqf[0], oqf[1]); w.y = cvt_pk_bf16(oqf[2], oqf[3]); w.z = cvt_pk_bf16(oqf[4], oqf[5]); w.w = cvt_pk_bf16(oqf[6], oqf[7]); *(u32x4*)(GQ + 0 * 4096 + lane * 64 + 8 * wid) = w;
;       w.x = cvt_pk_bf16(oqb[0], oqb[1]); w.y = cvt_pk_bf16(oqb[2], oqb[3]); w.z = cvt_pk_bf16(oqb[4], oqb[5]); w.w = cvt_pk_bf16(oqb[6], oqb[7]); *(u32x4*)(GQ + 1 * 4096 + lane * 64 + 8 * wid) = w;
;       w.x = cvt_pk_bf16(okf[0], okf[1]); w.y = cvt_pk_bf16(okf[2], okf[3]); w.z = cvt_pk_bf16(okf[4], okf[5]); w.w = cvt_pk_bf16(okf[6], okf[7]); *(u32x4*)(GQ + 2 * 4096 + lane * 64 + 8 * wid) = w;
;       w.x = cvt_pk_bf16(okb[0], okb[1]); w.y = cvt_pk_bf16(okb[2], okb[3]); w.z = cvt_pk_bf16(okb[4], okb[5]); w.w = cvt_pk_bf16(okb[6], okb[7]); *(u32x4*)(GQ + 3 * 4096 + lane * 64 + 8 * wid) = w; }
;     if (PROBE_CUT == 2 && dup) return;
;     __syncthreads();
;     { const int r32 = lane & 31, hi = lane >> 5, dir = wid >> 2, eb = wid & 3;
;       const LAS unsigned char* X = B + GB_VT; const LAS unsigned char* Y = B + (dir ? GB_QDB : GB_QDF);
;       f32x16 c0 = {}, c1 = {};
; #pragma unroll
;       for (int ks = 0; ks < 4; ++ks) { const bf16x8 av = ldfrag(X, 32 * eb + r32, ks, hi), b0 = ldfrag(Y, r32, ks, hi), b1 = ldfrag(Y, 32 + r32, ks, hi);
;           c0 = __builtin_amdgcn_mfma_f32_32x32x16_bf16(av, b0, c0, 0, 0, 0); c1 = __builtin_amdgcn_mfma_f32_32x32x16_bf16(av, b1, c1, 0, 0, 0); }
;       float* out = KVS + (size_t)(slot + dir) * 8192;
; #pragma unroll
;       for (int r = 0; r < 16; ++r) { const int e = 32 * eb + crow16(r, hi); out[e * 64 + r32] = c0[r]; out[e * 64 + 32 + r32] = c1[r]; } }
.LBB0_132:
	s_or_b64 exec, exec, s[14:15]
	v_mul_f32_e32 v15, 0xbfb8aa3b, v14
	v_mul_f32_e32 v16, 0xbfb8aa3b, v13
	v_exp_f32_e32 v15, v15
	v_exp_f32_e32 v16, v16
	v_mul_f32_e32 v13, 0x3fb8aa3b, v13
	v_mul_f32_e32 v17, 0xbfb8aa3b, v69
	v_mul_f32_e32 v15, v15, v9
	v_mul_f32_e32 v16, v16, v9
	v_mul_f32_e32 v9, 0x3fb8aa3b, v14
	v_mul_f32_e32 v18, 0xbfb8aa3b, v68
	v_exp_f32_e32 v9, v9
	v_exp_f32_e32 v13, v13
	v_exp_f32_e32 v17, v17
	v_exp_f32_e32 v18, v18
	v_and_b32_e32 v14, 0xffff0000, v5
	v_mul_f32_e32 v14, 0x3e000000, v14
	v_mul_f32_e32 v19, v14, v9
	v_mul_f32_e32 v9, v14, v13
	v_mul_f32_e32 v13, v17, v70
	v_mul_f32_e32 v14, v18, v70
	v_mul_f32_e32 v17, 0x3fb8aa3b, v69
	v_mul_f32_e32 v18, 0x3fb8aa3b, v68
	v_mul_f32_e32 v20, 0xbfb8aa3b, v67
	v_mul_f32_e32 v21, 0xbfb8aa3b, v66
	v_exp_f32_e32 v17, v17
	v_exp_f32_e32 v18, v18
	v_exp_f32_e32 v20, v20
	v_exp_f32_e32 v21, v21
	v_lshlrev_b32_e32 v5, 16, v5
	v_mul_f32_e32 v5, 0x3e000000, v5
	v_mul_f32_e32 v17, v5, v17
	v_mul_f32_e32 v5, v5, v18
	v_mul_f32_e32 v18, v20, v8
	v_mul_f32_e32 v20, v21, v8
	v_mul_f32_e32 v8, 0x3fb8aa3b, v67
	v_mul_f32_e32 v24, 0x3fb8aa3b, v66
	v_mul_f32_e32 v25, 0xbfb8aa3b, v64
	v_mul_f32_e32 v26, 0xbfb8aa3b, v63
	v_exp_f32_e32 v8, v8
	v_exp_f32_e32 v24, v24
	v_exp_f32_e32 v25, v25
	v_exp_f32_e32 v26, v26
	v_and_b32_e32 v21, 0xffff0000, v4
	v_mul_f32_e32 v21, 0x3e000000, v21
	v_mul_f32_e32 v27, v21, v8
	v_mul_f32_e32 v8, v21, v24
	v_mul_f32_e32 v21, v25, v65
	v_mul_f32_e32 v24, v26, v65
	v_mul_f32_e32 v25, 0x3fb8aa3b, v64
	v_mul_f32_e32 v26, 0x3fb8aa3b, v63
	v_mul_f32_e32 v28, 0xbfb8aa3b, v61
	v_mul_f32_e32 v29, 0xbfb8aa3b, v60
	v_exp_f32_e32 v25, v25
	v_exp_f32_e32 v26, v26
	v_exp_f32_e32 v28, v28
	v_exp_f32_e32 v29, v29
	v_lshlrev_b32_e32 v4, 16, v4
	v_mul_f32_e32 v4, 0x3e000000, v4
	v_mul_f32_e32 v25, v4, v25
	v_mul_f32_e32 v4, v4, v26
	v_mul_f32_e32 v26, v28, v62
	v_mul_f32_e32 v28, v29, v62
	v_mul_f32_e32 v29, 0x3fb8aa3b, v61
	v_mul_f32_e32 v31, 0x3fb8aa3b, v60
	v_mul_f32_e32 v32, 0xbfb8aa3b, v58
	v_mul_f32_e32 v33, 0xbfb8aa3b, v57
	v_exp_f32_e32 v29, v29
	v_exp_f32_e32 v31, v31
	v_exp_f32_e32 v32, v32
	v_exp_f32_e32 v33, v33
	v_and_b32_e32 v30, 0xffff0000, v3
	v_mul_f32_e32 v30, 0x3e000000, v30
	v_mul_f32_e32 v29, v30, v29
	v_mul_f32_e32 v30, v30, v31
	v_mul_f32_e32 v31, v32, v59
	v_mul_f32_e32 v32, v33, v59
	v_mul_f32_e32 v33, 0x3fb8aa3b, v58
	v_mul_f32_e32 v34, 0x3fb8aa3b, v57
	v_mul_f32_e32 v35, 0xbfb8aa3b, v55
	v_mul_f32_e32 v36, 0xbfb8aa3b, v54
	v_exp_f32_e32 v33, v33
	v_exp_f32_e32 v34, v34
	v_exp_f32_e32 v35, v35
	v_exp_f32_e32 v36, v36
	v_lshlrev_b32_e32 v3, 16, v3
	v_mul_f32_e32 v3, 0x3e000000, v3
	v_mul_f32_e32 v39, 0xbfb8aa3b, v11
	v_mul_f32_e32 v40, 0xbfb8aa3b, v10
	v_mul_f32_e32 v11, 0x3fb8aa3b, v11
	v_mul_f32_e32 v10, 0x3fb8aa3b, v10
	v_mul_f32_e32 v33, v3, v33
	v_mul_f32_e32 v3, v3, v34
	v_mul_f32_e32 v34, v35, v56
	v_mul_f32_e32 v35, v36, v56
	v_mul_f32_e32 v36, 0x3fb8aa3b, v55
	v_mul_f32_e32 v38, 0x3fb8aa3b, v54
	v_exp_f32_e32 v11, v11
	v_exp_f32_e32 v10, v10
	v_exp_f32_e32 v36, v36
	v_exp_f32_e32 v38, v38
	s_ashr_i32 s51, s50, 31
	v_and_b32_e32 v37, 0xffff0000, v2
	v_lshlrev_b32_e32 v2, 16, v2
	s_lshl_b64 s[4:5], s[50:51], 15
	v_mul_f32_e32 v2, 0x3e000000, v2
	s_add_u32 s4, s8, s4
	v_mul_f32_e32 v37, 0x3e000000, v37
	v_mul_f32_e32 v11, v2, v11
	v_mul_f32_e32 v2, v2, v10
	s_addc_u32 s5, s9, s5
	v_lshlrev_b32_e32 v0, 1, v0
	v_mul_f32_e32 v36, v37, v36
	v_mul_f32_e32 v37, v37, v38
	v_cvt_pk_bf16_f32 v2, v2, v37
	v_cvt_pk_bf16_f32 v3, v3, v30
	v_cvt_pk_bf16_f32 v4, v4, v8
	v_cvt_pk_bf16_f32 v5, v5, v9
	v_lshl_add_u64 v[8:9], s[4:5], 0, v[0:1]
	v_lshl_add_u64 v[6:7], v[6:7], 1, v[8:9]
	s_movk_i32 s4, 0x2000
	v_exp_f32_e32 v39, v39
	v_exp_f32_e32 v40, v40
	v_add_co_u32_e32 v8, vcc, s4, v6
	s_movk_i32 s4, 0x4000
	s_nop 0
	v_addc_co_u32_e32 v9, vcc, 0, v7, vcc
	global_store_dwordx4 v[6:7], v[2:5], off
	v_mul_f32_e32 v38, v39, v12
	v_mul_f32_e32 v12, v40, v12
	v_cvt_pk_bf16_f32 v2, v11, v36
	v_cvt_pk_bf16_f32 v3, v33, v29
	v_cvt_pk_bf16_f32 v4, v25, v27
	v_cvt_pk_bf16_f32 v5, v17, v19
	global_store_dwordx4 v[8:9], v[2:5], off
	v_add_co_u32_e32 v8, vcc, s4, v6
	s_movk_i32 s4, 0x6000
	s_nop 0
	v_addc_co_u32_e32 v9, vcc, 0, v7, vcc
	v_cvt_pk_bf16_f32 v2, v12, v35
	v_add_co_u32_e32 v6, vcc, s4, v6
	v_cvt_pk_bf16_f32 v3, v32, v28
	v_cvt_pk_bf16_f32 v4, v24, v20
	v_cvt_pk_bf16_f32 v5, v14, v16
	global_store_dwordx4 v[8:9], v[2:5], off
	s_nop 0
	v_addc_co_u32_e32 v7, vcc, 0, v7, vcc
	v_cvt_pk_bf16_f32 v2, v38, v34
	v_and_b32_e32 v0, 31, v23
	s_bfe_u32 s6, s91, 0x20006
	v_cvt_pk_bf16_f32 v3, v31, v26
	v_cvt_pk_bf16_f32 v4, v21, v18
	v_cvt_pk_bf16_f32 v5, v13, v15
	global_store_dwordx4 v[6:7], v[2:5], off
	v_lshrrev_b32_e32 v42, 5, v22
	s_waitcnt lgkmcnt(0)
	v_lshl_or_b32 v2, s6, 5, v0
	v_mul_u32_u24_e32 v2, 0x90, v2
	v_lshlrev_b32_e32 v3, 4, v42
	v_add3_u32 v43, s17, v2, v3
	s_barrier
	s_cmpk_lt_u32 s91, 0x100
	s_mov_b32 s4, 0x8200
	s_cselect_b32 s4, s4, 0xa600
	s_add_i32 s4, s4, 0
	v_mul_u32_u24_e32 v2, 0x90, v0
	v_add3_u32 v44, s4, v2, v3
	ds_read_b128 v[104:107], v43
	ds_read_b128 v[108:111], v44
	ds_read_b128 v[112:115], v44 offset:4608
	ds_read_b128 v[116:119], v43 offset:32
	ds_read_b128 v[120:123], v44 offset:32
	ds_read_b128 v[124:127], v44 offset:4640
	ds_read_b128 v[128:131], v43 offset:64
	ds_read_b128 v[132:135], v44 offset:64
	ds_read_b128 v[136:139], v44 offset:4672
	ds_read_b128 v[140:143], v43 offset:96
	ds_read_b128 v[144:147], v44 offset:96
	ds_read_b128 v[148:151], v44 offset:4704
	s_ashr_i32 s4, s91, 8
	s_add_i32 s4, s4, s20
	s_ashr_i32 s5, s4, 31
	s_lshl_b64 s[4:5], s[4:5], 15
	s_add_u32 s4, s69, s4
	s_addc_u32 s5, s70, s5
	s_lshl_b32 s6, s6, 11
	s_add_i32 s50, s50, s64
	s_cmpk_lt_i32 s50, 0x400
	s_cbranch_scc1 .Lp1_cmp
	s_sub_i32 s50, s50, 0xc0
	s_cmpk_lt_i32 s50, 0x400
	s_cbranch_scc0 .Lp1_cmp
	s_movk_i32 s50, 0x7fff
; #define LAS __attribute__((address_space(3)))
; __device__ __forceinline__ int crow16(int r, int hi) { return (r & 3) + 8 * (r >> 2) + 4 * hi; }
; __device__ __forceinline__ void gla_p1(CArgs& a, int l, int cc, int h, LAS float* L, int dup, bool stagew) {
;     ...
;     { const int r32 = lane & 31, hi = lane >> 5, dir = wid >> 2, eb = wid & 3;
;       const LAS unsigned char* X = B + GB_VT; const LAS unsigned char* Y = B + (dir ? GB_QDB : GB_QDF);
;       f32x16 c0 = {}, c1 = {};
; #pragma unroll
;       for (int ks = 0; ks < 4; ++ks) { const bf16x8 av = ldfrag(X, 32 * eb + r32, ks, hi), b0 = ldfrag(Y, r32, ks, hi), b1 = ldfrag(Y, 32 + r32, ks, hi);
;           c0 = __builtin_amdgcn_mfma_f32_32x32x16_bf16(av, b0, c0, 0, 0, 0); c1 = __builtin_amdgcn_mfma_f32_32x32x16_bf16(av, b1, c1, 0, 0, 0); }
;       float* out = KVS + (size_t)(slot + dir) * 8192;
; #pragma unroll
;       for (int r = 0; r < 16; ++r) { const int e = 32 * eb + crow16(r, hi); out[e * 64 + r32] = c0[r]; out[e * 64 + 32 + r32] = c1[r]; } }
.Lp1_cmp:
	s_cmpk_gt_i32 s50, 0x43f
	s_waitcnt lgkmcnt(10)
	v_mfma_f32_32x32x16_bf16 v[2:17], v[104:107], v[108:111], 0
	s_waitcnt lgkmcnt(9)
	v_mfma_f32_32x32x16_bf16 v[18:33], v[104:107], v[112:115], 0
	s_waitcnt lgkmcnt(7)
	v_mfma_f32_32x32x16_bf16 v[2:17], v[116:119], v[120:123], v[2:17]
	s_waitcnt lgkmcnt(6)
	v_mfma_f32_32x32x16_bf16 v[18:33], v[116:119], v[124:127], v[18:33]
	s_waitcnt lgkmcnt(4)
	v_mfma_f32_32x32x16_bf16 v[2:17], v[128:131], v[132:135], v[2:17]
	s_waitcnt lgkmcnt(3)
	v_mfma_f32_32x32x16_bf16 v[18:33], v[128:131], v[136:139], v[18:33]
	s_waitcnt lgkmcnt(1)
	v_mfma_f32_32x32x16_bf16 v[2:17], v[140:143], v[144:147], v[2:17]
	s_waitcnt lgkmcnt(0)
	v_mfma_f32_32x32x16_bf16 v[18:33], v[140:143], v[148:151], v[18:33]
	s_nop 1
	v_lshlrev_b32_e32 v34, 8, v42
	v_or3_b32 v0, s6, v34, v0
	v_lshlrev_b32_e32 v0, 2, v0
	v_lshl_add_u64 v[34:35], s[4:5], 0, v[0:1]
	s_nop 4
	global_store_dword v0, v2, s[4:5]
	s_nop 1
	global_store_dword v0, v18, s[4:5] offset:128
	global_store_dword v0, v3, s[4:5] offset:256
	global_store_dword v0, v19, s[4:5] offset:384
	global_store_dword v0, v4, s[4:5] offset:512
	global_store_dword v0, v20, s[4:5] offset:640
	global_store_dword v0, v5, s[4:5] offset:768
	global_store_dword v0, v21, s[4:5] offset:896
	global_store_dword v0, v6, s[4:5] offset:2048
	global_store_dword v0, v22, s[4:5] offset:2176
	global_store_dword v0, v7, s[4:5] offset:2304
	global_store_dword v0, v23, s[4:5] offset:2432
	global_store_dword v0, v8, s[4:5] offset:2560
	global_store_dword v0, v24, s[4:5] offset:2688
	global_store_dword v0, v9, s[4:5] offset:2816
	global_store_dword v0, v25, s[4:5] offset:2944
	v_add_co_u32_e32 v2, vcc, s10, v34
	s_mov_b32 s4, s71
	s_nop 0
	v_addc_co_u32_e32 v3, vcc, 0, v35, vcc
	global_store_dword v[2:3], v10, off
	global_store_dword v[2:3], v26, off offset:128
	global_store_dword v[2:3], v11, off offset:256
	global_store_dword v[2:3], v27, off offset:384
	global_store_dword v[2:3], v12, off offset:512
	global_store_dword v[2:3], v28, off offset:640
	global_store_dword v[2:3], v13, off offset:768
	global_store_dword v[2:3], v29, off offset:896
	global_store_dword v[2:3], v14, off offset:2048
	global_store_dword v[2:3], v30, off offset:2176
	global_store_dword v[2:3], v15, off offset:2304
	global_store_dword v[2:3], v31, off offset:2432
	global_store_dword v[2:3], v16, off offset:2560
	global_store_dword v[2:3], v32, off offset:2688
	global_store_dword v[2:3], v17, off offset:2816
	global_store_dword v[2:3], v33, off offset:2944
	s_cbranch_scc1 .LBB0_160
